# cross-attention: LDS reads pipelined in the remaining P*V stage too (all 8 stages)
# baseline (speedup 1.0000x reference)
; #define LAS __attribute__((address_space(3)))
; #define BAR_LDS() do { asm volatile("s_waitcnt lgkmcnt(0)" ::: "memory"); __builtin_amdgcn_s_barrier(); asm volatile("" ::: "memory"); } while (0)
; #define XA_PUT_K() do { _Pragma("unroll") for (int i = 0; i < 4; ++i) { const int cidx = tid + 512 * i, r = cidx >> 5, c8 = cidx & 31; *(LAS u32x4*)(Ks + r * KS + c8 * 8) = stg[i]; } } while (0)
; __device__ __forceinline__ void xattn_phase(KA a, LAS unsigned char* lds, int G, const int tid, const int bid) {
;     ...
;         const int qt = u >> 2, h = u & 3, row0 = qt * 128;
;         const int qrow = row0 + 16 * wid + fr;
;         bf16x8 qf[8];
; #pragma unroll
;         for (int ks = 0; ks < 8; ++ks) qf[ks] = __builtin_nontemporal_load((const bf16x8*)(Q + (size_t)qrow * 1024 + h * 256 + 32 * ks + 8 * fq));
;         f32x4 accS[16];
; #pragma unroll
;         for (int n = 0; n < 16; ++n) accS[n] = (f32x4){0.f, 0.f, 0.f, 0.f};
; #pragma unroll
;         for (int kt = 0; kt < 4; ++kt) {
;             BAR_LDS();
;             XA_PUT_K();
;             XA_FETCH(u, kt + 1);
;             BAR_LDS();
; #pragma unroll
;             for (int n = 0; n < 4; ++n)
; #pragma unroll
;                 for (int ks = 0; ks < 8; ++ks) { const bf16x8 kf = *(const LAS bf16x8*)(Ks + (16 * n + fr) * KS + 32 * ks + 8 * fq); accS[kt * 4 + n] = __builtin_amdgcn_mfma_f32_16x16x32_bf16(kf, qf[ks], accS[kt * 4 + n], 0, 0, 0); }
.LBB0_114:
	s_and_b32 s10, s18, 0xffffff80
	v_add_u32_e32 v0, s10, v133
	v_ashrrev_i32_e32 v1, 31, v0
	v_lshlrev_b64 v[118:119], 11, v[0:1]
	s_and_b32 s20, s19, 0x300
	v_lshl_add_u64 v[0:1], s[2:3], 0, v[118:119]
	s_lshl_b32 s30, s20, 1
	v_lshl_add_u64 v[0:1], v[0:1], 0, s[30:31]
	v_lshl_add_u64 v[0:1], v[0:1], 0, v[18:19]
	global_load_dwordx4 v[48:51], v[0:1], off nt
	global_load_dwordx4 v[44:47], v[0:1], off offset:64 nt
	global_load_dwordx4 v[40:43], v[0:1], off offset:128 nt
	global_load_dwordx4 v[36:39], v[0:1], off offset:192 nt
	global_load_dwordx4 v[32:35], v[0:1], off offset:256 nt
	global_load_dwordx4 v[28:31], v[0:1], off offset:320 nt
	global_load_dwordx4 v[4:7], v[0:1], off offset:384 nt
	s_nop 0
	global_load_dwordx4 v[0:3], v[0:1], off offset:448 nt
	s_ashr_i32 s21, s18, 31
	s_add_i32 s11, s18, 0xffffc000
	s_lshr_b32 s21, s21, 21
	s_lshr_b32 s11, s11, 12
	s_add_i32 s21, s10, s21
	s_add_i32 s11, s11, 8
	s_ashr_i32 s21, s21, 11
	s_cmpk_lt_i32 s10, 0x4000
	s_cselect_b32 s10, s21, s11
	s_lshl_b32 s10, s10, 8
	s_or_b32 s11, s10, 64
	s_waitcnt lgkmcnt(0)
	s_barrier
	s_waitcnt vmcnt(8)
	ds_write_b128 v145, v[20:23]
	ds_write_b128 v146, v[24:27]
	ds_write_b128 v147, v[8:11]
	ds_write_b128 v148, v[12:15]
	v_add_u32_e32 v8, s11, v128
	v_ashrrev_i32_e32 v9, 31, v8
	v_lshl_add_u64 v[84:85], v[16:17], 0, s[30:31]
	v_lshlrev_b64 v[8:9], 11, v[8:9]
	v_lshl_add_u64 v[8:9], v[84:85], 0, v[8:9]
	global_load_dwordx4 v[24:27], v[8:9], off
	v_add_u32_e32 v8, s11, v129
	v_ashrrev_i32_e32 v9, 31, v8
	v_lshlrev_b64 v[8:9], 11, v[8:9]
	v_lshl_add_u64 v[8:9], v[84:85], 0, v[8:9]
	global_load_dwordx4 v[52:55], v[8:9], off
	v_add_u32_e32 v8, s11, v130
	v_ashrrev_i32_e32 v9, 31, v8
	v_lshlrev_b64 v[8:9], 11, v[8:9]
	v_lshl_add_u64 v[8:9], v[84:85], 0, v[8:9]
	global_load_dwordx4 v[56:59], v[8:9], off
	v_add_u32_e32 v8, s11, v131
	v_ashrrev_i32_e32 v9, 31, v8
	v_lshlrev_b64 v[8:9], 11, v[8:9]
	v_lshl_add_u64 v[8:9], v[84:85], 0, v[8:9]
	global_load_dwordx4 v[60:63], v[8:9], off
	s_waitcnt lgkmcnt(0)
	s_barrier
	s_or_b32 s11, s10, 0x80
	v_add_u32_e32 v115, s20, v138
	s_movk_i32 s24, 0x3000
	v_add_u32_e32 v122, s20, v137
	v_add_u32_e32 v124, s20, v136
	v_add_u32_e32 v126, s20, v135
	v_add_u32_e32 v193, 0x8000, v140
	v_add_u32_e32 v194, 0x8000, v141
	v_add_u32_e32 v195, 0x8000, v142
	v_add_u32_e32 v196, 0xa000, v139
	v_add_u32_e32 v197, 0xa800, v139
	v_add_u32_e32 v198, 0xb000, v139
	v_add_u32_e32 v199, 0xb800, v139
	v_add_u32_e32 v200, 0xc800, v139
	v_add_u32_e32 v201, 0xd000, v139
	v_add_u32_e32 v202, 0xd800, v139
	v_add_u32_e32 v203, 0xe000, v139
	v_add_u32_e32 v204, 0xe800, v139
	v_add_u32_e32 v205, 0xf000, v139
	v_add_u32_e32 v206, 0xf800, v139
	s_waitcnt vmcnt(11)
	ds_read_b128 v[248:251], v149
	ds_read_b128 v[208:211], v149 offset:64
	ds_read_b128 v[212:215], v149 offset:128
	ds_read_b128 v[216:219], v149 offset:192
	ds_read_b128 v[220:223], v149 offset:256
	ds_read_b128 v[224:227], v149 offset:320
	ds_read_b128 v[228:231], v149 offset:384
	s_waitcnt lgkmcnt(6)
	v_mfma_f32_16x16x32_bf16 v[8:11], v[248:251], v[48:51], 0
	s_waitcnt vmcnt(10)
	ds_read_b128 v[232:235], v149 offset:448
	s_waitcnt lgkmcnt(6)
	v_mfma_f32_16x16x32_bf16 v[8:11], v[208:211], v[44:47], v[8:11]
	s_waitcnt vmcnt(9)
	ds_read_b128 v[236:239], v149 offset:8448
	s_waitcnt lgkmcnt(6)
	v_mfma_f32_16x16x32_bf16 v[8:11], v[212:215], v[40:43], v[8:11]
	s_waitcnt vmcnt(8)
	ds_read_b128 v[240:243], v149 offset:8512
	s_waitcnt lgkmcnt(6)
	v_mfma_f32_16x16x32_bf16 v[8:11], v[216:219], v[36:39], v[8:11]
	s_waitcnt vmcnt(7)
	ds_read_b128 v[244:247], v149 offset:8576
	s_waitcnt lgkmcnt(6)
	v_mfma_f32_16x16x32_bf16 v[8:11], v[220:223], v[32:35], v[8:11]
	s_waitcnt vmcnt(6)
	ds_read_b128 v[248:251], v149 offset:8640
	s_waitcnt lgkmcnt(6)
	v_mfma_f32_16x16x32_bf16 v[8:11], v[224:227], v[28:31], v[8:11]
	s_waitcnt vmcnt(5)
	ds_read_b128 v[208:211], v149 offset:8704
	s_waitcnt lgkmcnt(6)
	v_mfma_f32_16x16x32_bf16 v[8:11], v[228:231], v[4:7], v[8:11]
	s_waitcnt vmcnt(4)
	ds_read_b128 v[212:215], v149 offset:8768
	s_waitcnt lgkmcnt(6)
	v_mfma_f32_16x16x32_bf16 v[8:11], v[232:235], v[0:3], v[8:11]
	ds_read_b128 v[216:219], v149 offset:8832
	s_waitcnt lgkmcnt(6)
	v_mfma_f32_16x16x32_bf16 v[12:15], v[236:239], v[48:51], 0
	ds_read_b128 v[220:223], v149 offset:8896
	s_waitcnt lgkmcnt(6)
	v_mfma_f32_16x16x32_bf16 v[12:15], v[240:243], v[44:47], v[12:15]
	ds_read_b128 v[224:227], v149 offset:16896
	s_waitcnt lgkmcnt(6)
	v_mfma_f32_16x16x32_bf16 v[12:15], v[244:247], v[40:43], v[12:15]
	ds_read_b128 v[228:231], v149 offset:16960
	s_waitcnt lgkmcnt(6)
	v_mfma_f32_16x16x32_bf16 v[12:15], v[248:251], v[36:39], v[12:15]
	ds_read_b128 v[232:235], v149 offset:17024
	s_waitcnt lgkmcnt(6)
	v_mfma_f32_16x16x32_bf16 v[12:15], v[208:211], v[32:35], v[12:15]
	ds_read_b128 v[236:239], v149 offset:17088
	s_waitcnt lgkmcnt(6)
	v_mfma_f32_16x16x32_bf16 v[12:15], v[212:215], v[28:31], v[12:15]
	ds_read_b128 v[240:243], v149 offset:17152
	s_waitcnt lgkmcnt(6)
	v_mfma_f32_16x16x32_bf16 v[12:15], v[216:219], v[4:7], v[12:15]
	ds_read_b128 v[244:247], v149 offset:17216
	s_waitcnt lgkmcnt(6)
	v_mfma_f32_16x16x32_bf16 v[12:15], v[220:223], v[0:3], v[12:15]
	ds_read_b128 v[248:251], v149 offset:17280
	s_waitcnt lgkmcnt(6)
	v_mfma_f32_16x16x32_bf16 v[20:23], v[224:227], v[48:51], 0
	ds_read_b128 v[208:211], v149 offset:17344
	s_waitcnt lgkmcnt(6)
	v_mfma_f32_16x16x32_bf16 v[20:23], v[228:231], v[44:47], v[20:23]
	ds_read_b128 v[212:215], v149 offset:25344
	s_waitcnt lgkmcnt(6)
	v_mfma_f32_16x16x32_bf16 v[20:23], v[232:235], v[40:43], v[20:23]
	ds_read_b128 v[216:219], v149 offset:25408
	s_waitcnt lgkmcnt(6)
	v_mfma_f32_16x16x32_bf16 v[20:23], v[236:239], v[36:39], v[20:23]
	ds_read_b128 v[220:223], v149 offset:25472
	s_waitcnt lgkmcnt(6)
	v_mfma_f32_16x16x32_bf16 v[20:23], v[240:243], v[32:35], v[20:23]
	ds_read_b128 v[224:227], v149 offset:25536
	s_waitcnt lgkmcnt(6)
	v_mfma_f32_16x16x32_bf16 v[20:23], v[244:247], v[28:31], v[20:23]
	ds_read_b128 v[228:231], v149 offset:25600
	s_waitcnt lgkmcnt(6)
	v_mfma_f32_16x16x32_bf16 v[20:23], v[248:251], v[4:7], v[20:23]
	ds_read_b128 v[232:235], v149 offset:25664
	s_waitcnt lgkmcnt(6)
	v_mfma_f32_16x16x32_bf16 v[20:23], v[208:211], v[0:3], v[20:23]
	ds_read_b128 v[236:239], v149 offset:25728
	s_waitcnt lgkmcnt(6)
	v_mfma_f32_16x16x32_bf16 v[64:67], v[212:215], v[48:51], 0
	s_waitcnt lgkmcnt(5)
	v_mfma_f32_16x16x32_bf16 v[64:67], v[216:219], v[44:47], v[64:67]
	s_waitcnt lgkmcnt(4)
	v_mfma_f32_16x16x32_bf16 v[64:67], v[220:223], v[40:43], v[64:67]
	s_waitcnt lgkmcnt(3)
	v_mfma_f32_16x16x32_bf16 v[64:67], v[224:227], v[36:39], v[64:67]
	s_waitcnt lgkmcnt(2)
	v_mfma_f32_16x16x32_bf16 v[64:67], v[228:231], v[32:35], v[64:67]
	s_waitcnt lgkmcnt(1)
	v_mfma_f32_16x16x32_bf16 v[64:67], v[232:235], v[28:31], v[64:67]
	s_waitcnt lgkmcnt(0)
	v_mfma_f32_16x16x32_bf16 v[64:67], v[236:239], v[4:7], v[64:67]
	ds_read_b128 v[240:243], v149 offset:25792
	s_waitcnt lgkmcnt(0)
	s_barrier
; #define LAS __attribute__((address_space(3)))
; #define BAR_LDS() do { asm volatile("s_waitcnt lgkmcnt(0)" ::: "memory"); __builtin_amdgcn_s_barrier(); asm volatile("" ::: "memory"); } while (0)
; #define XA_PUT_K() do { _Pragma("unroll") for (int i = 0; i < 4; ++i) { const int cidx = tid + 512 * i, r = cidx >> 5, c8 = cidx & 31; *(LAS u32x4*)(Ks + r * KS + c8 * 8) = stg[i]; } } while (0)
; __device__ __forceinline__ void xattn_phase(KA a, LAS unsigned char* lds, int G, const int tid, const int bid) {
;     ...
;         for (int kt = 0; kt < 4; ++kt) {
;             BAR_LDS();
;             XA_PUT_K();
;             XA_FETCH(u, kt + 1);
;             BAR_LDS();
; #pragma unroll
;             for (int n = 0; n < 4; ++n)
; #pragma unroll
;                 for (int ks = 0; ks < 8; ++ks) { const bf16x8 kf = *(const LAS bf16x8*)(Ks + (16 * n + fr) * KS + 32 * ks + 8 * fq); accS[kt * 4 + n] = __builtin_amdgcn_mfma_f32_16x16x32_bf16(kf, qf[ks], accS[kt * 4 + n], 0, 0, 0); }
	s_waitcnt vmcnt(0)
	ds_write_b128 v145, v[60:63]
	ds_write_b128 v146, v[56:59]
	ds_write_b128 v147, v[52:55]
	ds_write_b128 v148, v[24:27]
	v_add_u32_e32 v24, s11, v128
	v_add_u32_e32 v52, s11, v129
	v_add_u32_e32 v56, s11, v130
	v_add_u32_e32 v60, s11, v131
	v_ashrrev_i32_e32 v25, 31, v24
	v_ashrrev_i32_e32 v53, 31, v52
	v_ashrrev_i32_e32 v57, 31, v56
	v_ashrrev_i32_e32 v61, 31, v60
	v_lshlrev_b64 v[24:25], 11, v[24:25]
	v_lshlrev_b64 v[52:53], 11, v[52:53]
	v_lshlrev_b64 v[56:57], 11, v[56:57]
	v_lshlrev_b64 v[60:61], 11, v[60:61]
	v_lshl_add_u64 v[24:25], v[84:85], 0, v[24:25]
	v_lshl_add_u64 v[52:53], v[84:85], 0, v[52:53]
	v_lshl_add_u64 v[56:57], v[84:85], 0, v[56:57]
	v_lshl_add_u64 v[60:61], v[84:85], 0, v[60:61]
	global_load_dwordx4 v[24:27], v[24:25], off
	s_waitcnt lgkmcnt(4)
	v_mfma_f32_16x16x32_bf16 v[64:67], v[240:243], v[0:3], v[64:67]
	global_load_dwordx4 v[52:55], v[52:53], off
	s_or_b32 s11, s10, 0xc0
	global_load_dwordx4 v[56:59], v[56:57], off
	s_nop 0
	global_load_dwordx4 v[60:63], v[60:61], off
	s_waitcnt lgkmcnt(0)
	s_barrier
	ds_read_b128 v[208:211], v149
	ds_read_b128 v[212:215], v149 offset:64
	ds_read_b128 v[216:219], v149 offset:128
	ds_read_b128 v[220:223], v149 offset:192
	ds_read_b128 v[224:227], v149 offset:256
	ds_read_b128 v[228:231], v149 offset:320
	ds_read_b128 v[232:235], v149 offset:384
	s_waitcnt lgkmcnt(6)
	v_mfma_f32_16x16x32_bf16 v[68:71], v[208:211], v[48:51], 0
	ds_read_b128 v[236:239], v149 offset:448
	s_waitcnt lgkmcnt(6)
	v_mfma_f32_16x16x32_bf16 v[68:71], v[212:215], v[44:47], v[68:71]
	ds_read_b128 v[240:243], v149 offset:8448
	s_waitcnt lgkmcnt(6)
	v_mfma_f32_16x16x32_bf16 v[68:71], v[216:219], v[40:43], v[68:71]
	ds_read_b128 v[244:247], v149 offset:8512
	s_waitcnt lgkmcnt(6)
	v_mfma_f32_16x16x32_bf16 v[68:71], v[220:223], v[36:39], v[68:71]
	ds_read_b128 v[248:251], v149 offset:8576
	s_waitcnt lgkmcnt(6)
	v_mfma_f32_16x16x32_bf16 v[68:71], v[224:227], v[32:35], v[68:71]
	ds_read_b128 v[208:211], v149 offset:8640
	s_waitcnt lgkmcnt(6)
	v_mfma_f32_16x16x32_bf16 v[68:71], v[228:231], v[28:31], v[68:71]
	ds_read_b128 v[212:215], v149 offset:8704
	s_waitcnt lgkmcnt(6)
	v_mfma_f32_16x16x32_bf16 v[68:71], v[232:235], v[4:7], v[68:71]
	ds_read_b128 v[216:219], v149 offset:8768
	s_waitcnt lgkmcnt(6)
	v_mfma_f32_16x16x32_bf16 v[68:71], v[236:239], v[0:3], v[68:71]
	ds_read_b128 v[220:223], v149 offset:8832
	s_waitcnt lgkmcnt(6)
	v_mfma_f32_16x16x32_bf16 v[72:75], v[240:243], v[48:51], 0
	ds_read_b128 v[224:227], v149 offset:8896
	s_waitcnt lgkmcnt(6)
	v_mfma_f32_16x16x32_bf16 v[72:75], v[244:247], v[44:47], v[72:75]
	ds_read_b128 v[228:231], v149 offset:16896
	s_waitcnt lgkmcnt(6)
	v_mfma_f32_16x16x32_bf16 v[72:75], v[248:251], v[40:43], v[72:75]
	ds_read_b128 v[232:235], v149 offset:16960
	s_waitcnt lgkmcnt(6)
	v_mfma_f32_16x16x32_bf16 v[72:75], v[208:211], v[36:39], v[72:75]
	ds_read_b128 v[236:239], v149 offset:17024
	s_waitcnt lgkmcnt(6)
	v_mfma_f32_16x16x32_bf16 v[72:75], v[212:215], v[32:35], v[72:75]
	ds_read_b128 v[240:243], v149 offset:17088
	s_waitcnt lgkmcnt(6)
	v_mfma_f32_16x16x32_bf16 v[72:75], v[216:219], v[28:31], v[72:75]
	ds_read_b128 v[244:247], v149 offset:17152
	s_waitcnt lgkmcnt(6)
	v_mfma_f32_16x16x32_bf16 v[72:75], v[220:223], v[4:7], v[72:75]
	ds_read_b128 v[248:251], v149 offset:17216
	s_waitcnt lgkmcnt(6)
	v_mfma_f32_16x16x32_bf16 v[72:75], v[224:227], v[0:3], v[72:75]
	ds_read_b128 v[208:211], v149 offset:17280
	s_waitcnt lgkmcnt(6)
	v_mfma_f32_16x16x32_bf16 v[76:79], v[228:231], v[48:51], 0
	ds_read_b128 v[212:215], v149 offset:17344
	s_waitcnt lgkmcnt(6)
	v_mfma_f32_16x16x32_bf16 v[76:79], v[232:235], v[44:47], v[76:79]
	ds_read_b128 v[216:219], v149 offset:25344
	s_waitcnt lgkmcnt(6)
	v_mfma_f32_16x16x32_bf16 v[76:79], v[236:239], v[40:43], v[76:79]
	ds_read_b128 v[220:223], v149 offset:25408
	s_waitcnt lgkmcnt(6)
	v_mfma_f32_16x16x32_bf16 v[76:79], v[240:243], v[36:39], v[76:79]
	ds_read_b128 v[224:227], v149 offset:25472
	s_waitcnt lgkmcnt(6)
	v_mfma_f32_16x16x32_bf16 v[76:79], v[244:247], v[32:35], v[76:79]
	ds_read_b128 v[228:231], v149 offset:25536
	s_waitcnt lgkmcnt(6)
	v_mfma_f32_16x16x32_bf16 v[76:79], v[248:251], v[28:31], v[76:79]
	ds_read_b128 v[232:235], v149 offset:25600
	s_waitcnt lgkmcnt(6)
	v_mfma_f32_16x16x32_bf16 v[76:79], v[208:211], v[4:7], v[76:79]
	ds_read_b128 v[236:239], v149 offset:25664
	s_waitcnt lgkmcnt(6)
	v_mfma_f32_16x16x32_bf16 v[76:79], v[212:215], v[0:3], v[76:79]
	ds_read_b128 v[240:243], v149 offset:25728
	s_waitcnt lgkmcnt(6)
	v_mfma_f32_16x16x32_bf16 v[80:83], v[216:219], v[48:51], 0
	s_waitcnt lgkmcnt(5)
	v_mfma_f32_16x16x32_bf16 v[80:83], v[220:223], v[44:47], v[80:83]
	s_waitcnt lgkmcnt(4)
	v_mfma_f32_16x16x32_bf16 v[80:83], v[224:227], v[40:43], v[80:83]
	s_waitcnt lgkmcnt(3)
	v_mfma_f32_16x16x32_bf16 v[80:83], v[228:231], v[36:39], v[80:83]
	s_waitcnt lgkmcnt(2)
	v_mfma_f32_16x16x32_bf16 v[80:83], v[232:235], v[32:35], v[80:83]
	s_waitcnt lgkmcnt(1)
	v_mfma_f32_16x16x32_bf16 v[80:83], v[236:239], v[28:31], v[80:83]
	s_waitcnt lgkmcnt(0)
	v_mfma_f32_16x16x32_bf16 v[80:83], v[240:243], v[4:7], v[80:83]
	ds_read_b128 v[244:247], v149 offset:25792
	s_waitcnt lgkmcnt(0)
	s_barrier
; #define LAS __attribute__((address_space(3)))
; #define BAR_LDS() do { asm volatile("s_waitcnt lgkmcnt(0)" ::: "memory"); __builtin_amdgcn_s_barrier(); asm volatile("" ::: "memory"); } while (0)
; #define XA_PUT_K() do { _Pragma("unroll") for (int i = 0; i < 4; ++i) { const int cidx = tid + 512 * i, r = cidx >> 5, c8 = cidx & 31; *(LAS u32x4*)(Ks + r * KS + c8 * 8) = stg[i]; } } while (0)
; __device__ __forceinline__ void xattn_phase(KA a, LAS unsigned char* lds, int G, const int tid, const int bid) {
;     ...
;         for (int kt = 0; kt < 4; ++kt) {
;             BAR_LDS();
;             XA_PUT_K();
;             XA_FETCH(u, kt + 1);
;             BAR_LDS();
; #pragma unroll
;             for (int n = 0; n < 4; ++n)
; #pragma unroll
;                 for (int ks = 0; ks < 8; ++ks) { const bf16x8 kf = *(const LAS bf16x8*)(Ks + (16 * n + fr) * KS + 32 * ks + 8 * fq); accS[kt * 4 + n] = __builtin_amdgcn_mfma_f32_16x16x32_bf16(kf, qf[ks], accS[kt * 4 + n], 0, 0, 0); }
	s_waitcnt vmcnt(0)
	ds_write_b128 v145, v[60:63]
	ds_write_b128 v146, v[56:59]
	ds_write_b128 v147, v[52:55]
	ds_write_b128 v148, v[24:27]
	v_add_u32_e32 v24, s11, v128
	v_add_u32_e32 v52, s11, v129
	v_add_u32_e32 v56, s11, v130
	v_add_u32_e32 v60, s11, v131
	v_ashrrev_i32_e32 v25, 31, v24
	v_ashrrev_i32_e32 v53, 31, v52
	v_ashrrev_i32_e32 v57, 31, v56
	v_ashrrev_i32_e32 v61, 31, v60
	v_lshlrev_b64 v[24:25], 11, v[24:25]
	v_lshlrev_b64 v[52:53], 11, v[52:53]
	v_lshlrev_b64 v[56:57], 11, v[56:57]
	v_lshlrev_b64 v[60:61], 11, v[60:61]
	v_lshl_add_u64 v[24:25], v[84:85], 0, v[24:25]
	v_lshl_add_u64 v[52:53], v[84:85], 0, v[52:53]
	v_lshl_add_u64 v[56:57], v[84:85], 0, v[56:57]
	v_lshl_add_u64 v[60:61], v[84:85], 0, v[60:61]
	global_load_dwordx4 v[24:27], v[24:25], off
	s_waitcnt lgkmcnt(4)
	v_mfma_f32_16x16x32_bf16 v[80:83], v[244:247], v[0:3], v[80:83]
	global_load_dwordx4 v[52:55], v[52:53], off
	s_ashr_i32 s11, s10, 31
	global_load_dwordx4 v[56:59], v[56:57], off
	s_lshl_b64 s[10:11], s[10:11], 1
	global_load_dwordx4 v[60:63], v[60:61], off
	s_waitcnt lgkmcnt(0)
	s_barrier
	ds_read_b128 v[248:251], v149
	ds_read_b128 v[208:211], v149 offset:64
	ds_read_b128 v[212:215], v149 offset:128
	ds_read_b128 v[216:219], v149 offset:192
	ds_read_b128 v[220:223], v149 offset:256
	ds_read_b128 v[224:227], v149 offset:320
	ds_read_b128 v[228:231], v149 offset:384
	s_waitcnt lgkmcnt(6)
	v_mfma_f32_16x16x32_bf16 v[84:87], v[248:251], v[48:51], 0
	ds_read_b128 v[232:235], v149 offset:448
	s_waitcnt lgkmcnt(6)
	v_mfma_f32_16x16x32_bf16 v[84:87], v[208:211], v[44:47], v[84:87]
	ds_read_b128 v[236:239], v149 offset:8448
	s_waitcnt lgkmcnt(6)
	v_mfma_f32_16x16x32_bf16 v[84:87], v[212:215], v[40:43], v[84:87]
	ds_read_b128 v[240:243], v149 offset:8512
	s_waitcnt lgkmcnt(6)
	v_mfma_f32_16x16x32_bf16 v[84:87], v[216:219], v[36:39], v[84:87]
	ds_read_b128 v[244:247], v149 offset:8576
	s_waitcnt lgkmcnt(6)
	v_mfma_f32_16x16x32_bf16 v[84:87], v[220:223], v[32:35], v[84:87]
	ds_read_b128 v[248:251], v149 offset:8640
	s_waitcnt lgkmcnt(6)
	v_mfma_f32_16x16x32_bf16 v[84:87], v[224:227], v[28:31], v[84:87]
	ds_read_b128 v[208:211], v149 offset:8704
	s_waitcnt lgkmcnt(6)
	v_mfma_f32_16x16x32_bf16 v[84:87], v[228:231], v[4:7], v[84:87]
	ds_read_b128 v[212:215], v149 offset:8768
	s_waitcnt lgkmcnt(6)
	v_mfma_f32_16x16x32_bf16 v[84:87], v[232:235], v[0:3], v[84:87]
	ds_read_b128 v[216:219], v149 offset:8832
	s_waitcnt lgkmcnt(6)
	v_mfma_f32_16x16x32_bf16 v[88:91], v[236:239], v[48:51], 0
	ds_read_b128 v[220:223], v149 offset:8896
	s_waitcnt lgkmcnt(6)
	v_mfma_f32_16x16x32_bf16 v[88:91], v[240:243], v[44:47], v[88:91]
	ds_read_b128 v[224:227], v149 offset:16896
	s_waitcnt lgkmcnt(6)
	v_mfma_f32_16x16x32_bf16 v[88:91], v[244:247], v[40:43], v[88:91]
	ds_read_b128 v[228:231], v149 offset:16960
	s_waitcnt lgkmcnt(6)
	v_mfma_f32_16x16x32_bf16 v[88:91], v[248:251], v[36:39], v[88:91]
	ds_read_b128 v[232:235], v149 offset:17024
	s_waitcnt lgkmcnt(6)
	v_mfma_f32_16x16x32_bf16 v[88:91], v[208:211], v[32:35], v[88:91]
	ds_read_b128 v[236:239], v149 offset:17088
	s_waitcnt lgkmcnt(6)
	v_mfma_f32_16x16x32_bf16 v[88:91], v[212:215], v[28:31], v[88:91]
	ds_read_b128 v[240:243], v149 offset:17152
	s_waitcnt lgkmcnt(6)
	v_mfma_f32_16x16x32_bf16 v[88:91], v[216:219], v[4:7], v[88:91]
	ds_read_b128 v[244:247], v149 offset:17216
	s_waitcnt lgkmcnt(6)
	v_mfma_f32_16x16x32_bf16 v[88:91], v[220:223], v[0:3], v[88:91]
	ds_read_b128 v[248:251], v149 offset:17280
	s_waitcnt lgkmcnt(6)
	v_mfma_f32_16x16x32_bf16 v[92:95], v[224:227], v[48:51], 0
	ds_read_b128 v[208:211], v149 offset:17344
	s_waitcnt lgkmcnt(6)
	v_mfma_f32_16x16x32_bf16 v[92:95], v[228:231], v[44:47], v[92:95]
	ds_read_b128 v[212:215], v149 offset:25344
	s_waitcnt lgkmcnt(6)
	v_mfma_f32_16x16x32_bf16 v[92:95], v[232:235], v[40:43], v[92:95]
	ds_read_b128 v[216:219], v149 offset:25408
	s_waitcnt lgkmcnt(6)
	v_mfma_f32_16x16x32_bf16 v[92:95], v[236:239], v[36:39], v[92:95]
	ds_read_b128 v[220:223], v149 offset:25472
	s_waitcnt lgkmcnt(6)
	v_mfma_f32_16x16x32_bf16 v[92:95], v[240:243], v[32:35], v[92:95]
	ds_read_b128 v[224:227], v149 offset:25536
	s_waitcnt lgkmcnt(6)
	v_mfma_f32_16x16x32_bf16 v[92:95], v[244:247], v[28:31], v[92:95]
	ds_read_b128 v[228:231], v149 offset:25600
	s_waitcnt lgkmcnt(6)
	v_mfma_f32_16x16x32_bf16 v[92:95], v[248:251], v[4:7], v[92:95]
	ds_read_b128 v[232:235], v149 offset:25664
	s_waitcnt lgkmcnt(6)
	v_mfma_f32_16x16x32_bf16 v[92:95], v[208:211], v[0:3], v[92:95]
	ds_read_b128 v[236:239], v149 offset:25728
	s_waitcnt lgkmcnt(6)
	v_mfma_f32_16x16x32_bf16 v[96:99], v[212:215], v[48:51], 0
	s_waitcnt lgkmcnt(5)
	v_mfma_f32_16x16x32_bf16 v[96:99], v[216:219], v[44:47], v[96:99]
	s_waitcnt lgkmcnt(4)
	v_mfma_f32_16x16x32_bf16 v[96:99], v[220:223], v[40:43], v[96:99]
	s_waitcnt lgkmcnt(3)
	v_mfma_f32_16x16x32_bf16 v[96:99], v[224:227], v[36:39], v[96:99]
	s_waitcnt lgkmcnt(2)
	v_mfma_f32_16x16x32_bf16 v[96:99], v[228:231], v[32:35], v[96:99]
	s_waitcnt lgkmcnt(1)
	v_mfma_f32_16x16x32_bf16 v[96:99], v[232:235], v[28:31], v[96:99]
	s_waitcnt lgkmcnt(0)
	v_mfma_f32_16x16x32_bf16 v[96:99], v[236:239], v[4:7], v[96:99]
	ds_read_b128 v[240:243], v149 offset:25792
	s_waitcnt lgkmcnt(0)
	s_barrier
	s_waitcnt vmcnt(0)
	ds_write_b128 v145, v[60:63]
	ds_write_b128 v146, v[56:59]
	ds_write_b128 v147, v[52:55]
	ds_write_b128 v148, v[24:27]
	v_lshl_add_u64 v[60:61], v[112:113], 0, s[10:11]
	v_mad_i64_i32 v[24:25], s[22:23], v115, s24, v[60:61]
	v_mad_i64_i32 v[52:53], s[22:23], v122, s24, v[60:61]
	v_mad_i64_i32 v[56:57], s[22:23], v124, s24, v[60:61]
	v_mad_i64_i32 v[60:61], s[20:21], v126, s24, v[60:61]
	global_load_dwordx4 v[24:27], v[24:25], off
	s_waitcnt lgkmcnt(4)
	v_mfma_f32_16x16x32_bf16 v[96:99], v[240:243], v[0:3], v[96:99]
	global_load_dwordx4 v[52:55], v[52:53], off
	s_mov_b32 s20, 0xff61b1e6
	global_load_dwordx4 v[56:59], v[56:57], off
	s_add_u32 s10, s6, s10
	global_load_dwordx4 v[60:63], v[60:61], off
	s_waitcnt lgkmcnt(0)
	s_barrier
; #define LAS __attribute__((address_space(3)))
; __device__ __forceinline__ void xattn_phase(KA a, LAS unsigned char* lds, int G, const int tid, const int bid) {
;     ...
; #pragma unroll
;             for (int n = 0; n < 4; ++n)
; #pragma unroll
;                 for (int ks = 0; ks < 8; ++ks) { const bf16x8 kf = *(const LAS bf16x8*)(Ks + (16 * n + fr) * KS + 32 * ks + 8 * fq); accS[kt * 4 + n] = __builtin_amdgcn_mfma_f32_16x16x32_bf16(kf, qf[ks], accS[kt * 4 + n], 0, 0, 0); }
	ds_read_b128 v[244:247], v149
	ds_read_b128 v[248:251], v149 offset:64
	ds_read_b128 v[208:211], v149 offset:128
	ds_read_b128 v[212:215], v149 offset:192
	ds_read_b128 v[216:219], v149 offset:256
	ds_read_b128 v[220:223], v149 offset:320
	ds_read_b128 v[224:227], v149 offset:384
	s_waitcnt lgkmcnt(6)
	v_mfma_f32_16x16x32_bf16 v[100:103], v[244:247], v[48:51], 0
	s_addc_u32 s11, s7, s11
	ds_read_b128 v[228:231], v149 offset:448
	s_waitcnt lgkmcnt(6)
	v_mfma_f32_16x16x32_bf16 v[100:103], v[248:251], v[44:47], v[100:103]
	s_cmpk_lt_i32 s16, 0xa00
	ds_read_b128 v[232:235], v149 offset:8448
	s_waitcnt lgkmcnt(6)
	v_mfma_f32_16x16x32_bf16 v[100:103], v[208:211], v[40:43], v[100:103]
	ds_read_b128 v[236:239], v149 offset:8512
	s_waitcnt lgkmcnt(6)
	v_mfma_f32_16x16x32_bf16 v[100:103], v[212:215], v[36:39], v[100:103]
	ds_read_b128 v[240:243], v149 offset:8576
	s_waitcnt lgkmcnt(6)
	v_mfma_f32_16x16x32_bf16 v[100:103], v[216:219], v[32:35], v[100:103]
	ds_read_b128 v[244:247], v149 offset:8640
	s_waitcnt lgkmcnt(6)
	v_mfma_f32_16x16x32_bf16 v[100:103], v[220:223], v[28:31], v[100:103]
	ds_read_b128 v[248:251], v149 offset:8704
	s_waitcnt lgkmcnt(6)
	v_mfma_f32_16x16x32_bf16 v[100:103], v[224:227], v[4:7], v[100:103]
	ds_read_b128 v[208:211], v149 offset:8768
	s_waitcnt lgkmcnt(6)
	v_mfma_f32_16x16x32_bf16 v[100:103], v[228:231], v[0:3], v[100:103]
	ds_read_b128 v[212:215], v149 offset:8832
	s_waitcnt lgkmcnt(6)
	v_mfma_f32_16x16x32_bf16 v[104:107], v[232:235], v[48:51], 0
	ds_read_b128 v[216:219], v149 offset:8896
	s_waitcnt lgkmcnt(6)
	v_mfma_f32_16x16x32_bf16 v[104:107], v[236:239], v[44:47], v[104:107]
	ds_read_b128 v[220:223], v149 offset:16896
	s_waitcnt lgkmcnt(6)
	v_mfma_f32_16x16x32_bf16 v[104:107], v[240:243], v[40:43], v[104:107]
	ds_read_b128 v[224:227], v149 offset:16960
	s_waitcnt lgkmcnt(6)
	v_mfma_f32_16x16x32_bf16 v[104:107], v[244:247], v[36:39], v[104:107]
	ds_read_b128 v[228:231], v149 offset:17024
	s_waitcnt lgkmcnt(6)
	v_mfma_f32_16x16x32_bf16 v[104:107], v[248:251], v[32:35], v[104:107]
	ds_read_b128 v[232:235], v149 offset:17088
	s_waitcnt lgkmcnt(6)
	v_mfma_f32_16x16x32_bf16 v[104:107], v[208:211], v[28:31], v[104:107]
	ds_read_b128 v[236:239], v149 offset:17152
	s_waitcnt lgkmcnt(6)
	v_mfma_f32_16x16x32_bf16 v[104:107], v[212:215], v[4:7], v[104:107]
	ds_read_b128 v[240:243], v149 offset:17216
	s_waitcnt lgkmcnt(6)
	v_mfma_f32_16x16x32_bf16 v[104:107], v[216:219], v[0:3], v[104:107]
	ds_read_b128 v[244:247], v149 offset:17280
	s_waitcnt lgkmcnt(6)
	v_mfma_f32_16x16x32_bf16 v[108:111], v[220:223], v[48:51], 0
	ds_read_b128 v[248:251], v149 offset:17344
	s_waitcnt lgkmcnt(6)
	v_mfma_f32_16x16x32_bf16 v[108:111], v[224:227], v[44:47], v[108:111]
	ds_read_b128 v[208:211], v149 offset:25344
	s_waitcnt lgkmcnt(6)
	v_mfma_f32_16x16x32_bf16 v[108:111], v[228:231], v[40:43], v[108:111]
	ds_read_b128 v[212:215], v149 offset:25408
	s_waitcnt lgkmcnt(6)
	v_mfma_f32_16x16x32_bf16 v[108:111], v[232:235], v[36:39], v[108:111]
	ds_read_b128 v[216:219], v149 offset:25472
	s_waitcnt lgkmcnt(6)
	v_mfma_f32_16x16x32_bf16 v[108:111], v[236:239], v[32:35], v[108:111]
	ds_read_b128 v[220:223], v149 offset:25536
	s_waitcnt lgkmcnt(6)
	v_mfma_f32_16x16x32_bf16 v[108:111], v[240:243], v[28:31], v[108:111]
	ds_read_b128 v[224:227], v149 offset:25600
	s_waitcnt lgkmcnt(6)
	v_mfma_f32_16x16x32_bf16 v[108:111], v[244:247], v[4:7], v[108:111]
	ds_read_b128 v[228:231], v149 offset:25664
	s_waitcnt lgkmcnt(6)
	v_mfma_f32_16x16x32_bf16 v[108:111], v[248:251], v[0:3], v[108:111]
	ds_read_b128 v[232:235], v149 offset:25728
	s_waitcnt lgkmcnt(6)
	v_mfma_f32_16x16x32_bf16 v[48:51], v[208:211], v[48:51], 0
	s_waitcnt lgkmcnt(5)
	v_mfma_f32_16x16x32_bf16 v[44:47], v[212:215], v[44:47], v[48:51]
	s_nop 4
	s_waitcnt lgkmcnt(4)
	v_mfma_f32_16x16x32_bf16 v[40:43], v[216:219], v[40:43], v[44:47]
	s_nop 2
	s_waitcnt lgkmcnt(3)
	v_mfma_f32_16x16x32_bf16 v[36:39], v[220:223], v[36:39], v[40:43]
	s_nop 2
	s_waitcnt lgkmcnt(2)
	v_mfma_f32_16x16x32_bf16 v[32:35], v[224:227], v[32:35], v[36:39]
	s_nop 2
	s_waitcnt lgkmcnt(1)
	v_mfma_f32_16x16x32_bf16 v[28:31], v[228:231], v[28:31], v[32:35]
	s_nop 2
	s_waitcnt lgkmcnt(0)
	v_mfma_f32_16x16x32_bf16 v[4:7], v[232:235], v[4:7], v[28:31]
	s_nop 2
	ds_read_b128 v[236:239], v149 offset:25792
	s_waitcnt lgkmcnt(0)
	s_barrier
; __device__ __forceinline__ void xattn_phase(KA a, LAS unsigned char* lds, int G, const int tid, const int bid) {
;     ...
;         float mx = -3.0e38f;
; #pragma unroll
;         for (int n = 0; n < 16; ++n)
; #pragma unroll
;             for (int i = 0; i < 4; ++i) mx = fmaxf(mx, accS[n][i]);
;         mx = fmaxf(mx, __shfl_xor(mx, 16)); mx = fmaxf(mx, __shfl_xor(mx, 32));
;         float sum = 0.f;
; #pragma unroll
;         for (int n = 0; n < 16; ++n)
; #pragma unroll
;             for (int i = 0; i < 4; ++i) { const float p = __builtin_amdgcn_exp2f(accS[n][i] - mx); accS[n][i] = p; sum += p; }
;         sum += __shfl_xor(sum, 16); sum += __shfl_xor(sum, 32);
	s_waitcnt lgkmcnt(0)
	v_mfma_f32_16x16x32_bf16 v[0:3], v[236:239], v[0:3], v[4:7]
	s_nop 2
	v_max3_f32 v4, v8, s20, v9
	v_max3_f32 v4, v4, v10, v11
	v_max3_f32 v4, v4, v12, v13
	v_max3_f32 v4, v4, v14, v15
	v_max3_f32 v4, v4, v20, v21
	v_max3_f32 v4, v4, v22, v23
	v_max3_f32 v4, v4, v64, v65
	v_max3_f32 v4, v4, v66, v67
	v_max3_f32 v4, v4, v68, v69
	v_max3_f32 v4, v4, v70, v71
	v_max3_f32 v4, v4, v72, v73
	v_max3_f32 v4, v4, v74, v75
	v_max3_f32 v4, v4, v76, v77
	v_max3_f32 v4, v4, v78, v79
	v_max3_f32 v4, v4, v80, v81
	v_max3_f32 v4, v4, v82, v83
	v_max3_f32 v4, v4, v84, v85
	v_max3_f32 v4, v4, v86, v87
	v_max3_f32 v4, v4, v88, v89
	v_max3_f32 v4, v4, v90, v91
	v_max3_f32 v4, v4, v92, v93
	v_max3_f32 v4, v4, v94, v95
	v_max3_f32 v4, v4, v96, v97
	v_max3_f32 v4, v4, v98, v99
	v_max3_f32 v4, v4, v100, v101
	v_max3_f32 v4, v4, v102, v103
	v_max3_f32 v4, v4, v104, v105
	v_max3_f32 v4, v4, v106, v107
	v_max3_f32 v4, v4, v108, v109
	v_xor_b32_e32 v5, 16, v164
	v_max3_f32 v4, v4, v110, v111
	v_cmp_lt_i32_e32 vcc, v5, v166
	v_max3_f32 v4, v4, v0, v1
	v_max3_f32 v4, v4, v2, v3
	v_cndmask_b32_e32 v5, v164, v5, vcc
	v_lshlrev_b32_e32 v5, 2, v5
	ds_bpermute_b32 v6, v5, v4
	s_waitcnt vmcnt(0)
	ds_write2_b64 v150, v[60:61], v[62:63] offset1:1
	ds_write2_b64 v151, v[56:57], v[58:59] offset1:1
	ds_write2_b64 v152, v[52:53], v[54:55] offset1:1
	ds_write2_b64 v153, v[24:25], v[26:27] offset1:1
	s_waitcnt lgkmcnt(4)
	v_max_f32_e32 v6, v6, v6
	v_max_f32_e32 v4, v4, v6
	v_xor_b32_e32 v6, 32, v164
	v_cmp_lt_i32_e32 vcc, v6, v166
	s_nop 1
	v_cndmask_b32_e32 v6, v164, v6, vcc
	v_lshlrev_b32_e32 v6, 2, v6
	ds_bpermute_b32 v7, v6, v4
	s_waitcnt lgkmcnt(0)
	v_max_f32_e32 v7, v7, v7
	v_max_f32_e32 v4, v4, v7
	v_sub_f32_e32 v7, v8, v4
	v_exp_f32_e32 v7, v7
	v_sub_f32_e32 v9, v9, v4
	v_exp_f32_e32 v9, v9
	v_sub_f32_e32 v10, v10, v4
	v_exp_f32_e32 v10, v10
	v_sub_f32_e32 v11, v11, v4
	v_exp_f32_e32 v11, v11
	v_sub_f32_e32 v12, v12, v4
	v_add_f32_e32 v8, 0, v7
	v_exp_f32_e32 v12, v12
	v_sub_f32_e32 v13, v13, v4
	v_add_f32_e32 v8, v9, v8
	v_exp_f32_e32 v13, v13
	v_sub_f32_e32 v14, v14, v4
	v_add_f32_e32 v8, v10, v8
	v_exp_f32_e32 v14, v14
	v_sub_f32_e32 v15, v15, v4
	v_add_f32_e32 v8, v11, v8
	v_exp_f32_e32 v15, v15
	v_sub_f32_e32 v20, v20, v4
	v_add_f32_e32 v8, v12, v8
	v_exp_f32_e32 v20, v20
	v_sub_f32_e32 v21, v21, v4
	v_add_f32_e32 v8, v13, v8
	v_exp_f32_e32 v21, v21
	v_sub_f32_e32 v22, v22, v4
	v_add_f32_e32 v8, v14, v8
	v_exp_f32_e32 v22, v22
	v_sub_f32_e32 v23, v23, v4
	v_add_f32_e32 v8, v15, v8
	v_exp_f32_e32 v23, v23
	v_sub_f32_e32 v28, v64, v4
	v_add_f32_e32 v8, v20, v8
	v_exp_f32_e32 v32, v28
	v_sub_f32_e32 v28, v65, v4
	v_add_f32_e32 v8, v21, v8
	v_exp_f32_e32 v33, v28
	v_sub_f32_e32 v28, v66, v4
	v_add_f32_e32 v8, v22, v8
	v_exp_f32_e32 v34, v28
	v_sub_f32_e32 v28, v67, v4
	v_add_f32_e32 v8, v23, v8
	v_exp_f32_e32 v35, v28
	v_sub_f32_e32 v28, v68, v4
	v_add_f32_e32 v8, v32, v8
	v_exp_f32_e32 v36, v28
	v_sub_f32_e32 v28, v69, v4
	v_add_f32_e32 v8, v33, v8
	v_exp_f32_e32 v37, v28
	v_sub_f32_e32 v28, v70, v4
	v_add_f32_e32 v8, v34, v8
	v_exp_f32_e32 v38, v28
	v_sub_f32_e32 v28, v71, v4
	v_add_f32_e32 v8, v35, v8
	v_exp_f32_e32 v39, v28
	v_sub_f32_e32 v28, v72, v4
	v_add_f32_e32 v8, v36, v8
	v_exp_f32_e32 v40, v28
	v_sub_f32_e32 v28, v73, v4
	v_add_f32_e32 v8, v37, v8
	v_exp_f32_e32 v41, v28
	v_sub_f32_e32 v28, v74, v4
	v_add_f32_e32 v8, v38, v8
	v_exp_f32_e32 v42, v28
	v_sub_f32_e32 v28, v75, v4
	v_add_f32_e32 v8, v39, v8
	v_exp_f32_e32 v43, v28
	v_sub_f32_e32 v28, v76, v4
	v_add_f32_e32 v8, v40, v8
	v_exp_f32_e32 v44, v28
	v_sub_f32_e32 v28, v77, v4
	v_add_f32_e32 v8, v41, v8
	v_exp_f32_e32 v45, v28
	v_sub_f32_e32 v28, v78, v4
	v_add_f32_e32 v8, v42, v8
	v_exp_f32_e32 v46, v28
	v_sub_f32_e32 v28, v79, v4
	v_add_f32_e32 v8, v43, v8
	v_exp_f32_e32 v47, v28
	v_sub_f32_e32 v28, v80, v4
	v_add_f32_e32 v8, v44, v8
	v_exp_f32_e32 v48, v28
	v_sub_f32_e32 v28, v81, v4
	v_add_f32_e32 v8, v45, v8
	v_exp_f32_e32 v49, v28
	v_sub_f32_e32 v28, v82, v4
	v_add_f32_e32 v8, v46, v8
	v_exp_f32_e32 v50, v28
	v_sub_f32_e32 v28, v83, v4
	v_add_f32_e32 v8, v47, v8
	v_exp_f32_e32 v51, v28
	v_sub_f32_e32 v28, v84, v4
	v_add_f32_e32 v8, v48, v8
	v_exp_f32_e32 v64, v28
	v_sub_f32_e32 v28, v85, v4
	v_add_f32_e32 v8, v49, v8
	v_exp_f32_e32 v65, v28
	v_sub_f32_e32 v28, v86, v4
	v_add_f32_e32 v8, v50, v8
	v_exp_f32_e32 v66, v28
	v_sub_f32_e32 v28, v87, v4
	v_add_f32_e32 v8, v51, v8
	v_exp_f32_e32 v67, v28
	v_sub_f32_e32 v28, v88, v4
	v_add_f32_e32 v8, v64, v8
	v_exp_f32_e32 v68, v28
	v_sub_f32_e32 v28, v89, v4
	v_add_f32_e32 v8, v65, v8
	v_exp_f32_e32 v69, v28
	v_sub_f32_e32 v28, v90, v4
	v_add_f32_e32 v8, v66, v8
	v_exp_f32_e32 v70, v28
	v_sub_f32_e32 v28, v91, v4
	v_add_f32_e32 v8, v67, v8
	v_exp_f32_e32 v71, v28
	v_sub_f32_e32 v28, v92, v4
	v_add_f32_e32 v8, v68, v8
	v_exp_f32_e32 v72, v28
	v_sub_f32_e32 v28, v93, v4
	v_add_f32_e32 v8, v69, v8
	v_exp_f32_e32 v73, v28
	v_sub_f32_e32 v28, v94, v4
	v_add_f32_e32 v8, v70, v8
	v_exp_f32_e32 v74, v28
	v_sub_f32_e32 v28, v95, v4
	v_add_f32_e32 v8, v71, v8
	v_exp_f32_e32 v75, v28
	v_sub_f32_e32 v28, v96, v4
	v_add_f32_e32 v8, v72, v8
	v_exp_f32_e32 v76, v28
	v_sub_f32_e32 v28, v97, v4
	v_add_f32_e32 v8, v73, v8
	v_exp_f32_e32 v77, v28
	v_sub_f32_e32 v28, v98, v4
	v_add_f32_e32 v8, v74, v8
	v_exp_f32_e32 v78, v28
	v_sub_f32_e32 v28, v99, v4
	v_add_f32_e32 v8, v75, v8
	v_exp_f32_e32 v79, v28
	v_sub_f32_e32 v28, v100, v4
	v_add_f32_e32 v8, v76, v8
	v_exp_f32_e32 v117, v28
	v_sub_f32_e32 v28, v101, v4
	v_add_f32_e32 v8, v77, v8
	v_exp_f32_e32 v154, v28
	v_sub_f32_e32 v28, v102, v4
	v_add_f32_e32 v8, v78, v8
	v_exp_f32_e32 v155, v28
; #define LAS __attribute__((address_space(3)))
; __device__ __forceinline__ unsigned pk2(float lo, float hi) { const f32x2 v = {lo, hi}; return __builtin_bit_cast(unsigned, __builtin_convertvector(v, bf16x2_t)); }
; #define BAR_LDS() do { asm volatile("s_waitcnt lgkmcnt(0)" ::: "memory"); __builtin_amdgcn_s_barrier(); asm volatile("" ::: "memory"); } while (0)
; #define XA_PUT_V() do { _Pragma("unroll") for (int i = 0; i < 4; ++i) { const int cidx = tid + 512 * i, r = cidx >> 3, c8 = cidx & 7; *(LAS u32x2*)(Vs + r * VS + c8 * 8) = (u32x2){stg[i].x, stg[i].y}; *(LAS u32x2*)(Vs + r * VS + c8 * 8 + 4) = (u32x2){stg[i].z, stg[i].w}; } } while (0)
; __device__ __forceinline__ void xattn_phase(KA a, LAS unsigned char* lds, int G, const int tid, const int bid) {
;     ...
;         for (int n = 0; n < 16; ++n)
; #pragma unroll
;             for (int i = 0; i < 4; ++i) { const float p = __builtin_amdgcn_exp2f(accS[n][i] - mx); accS[n][i] = p; sum += p; }
;         sum += __shfl_xor(sum, 16); sum += __shfl_xor(sum, 32);
;         const float inv = __builtin_amdgcn_rcpf(sum);
;         bf16x8 pf[8];
; #pragma unroll
;         for (int kb = 0; kb < 8; ++kb) { u32x4 w; w.x = pk2(accS[2 * kb][0], accS[2 * kb][1]); w.y = pk2(accS[2 * kb][2], accS[2 * kb][3]); w.z = pk2(accS[2 * kb + 1][0], accS[2 * kb + 1][1]); w.w = pk2(accS[2 * kb + 1][2], accS[2 * kb + 1][3]); pf[kb] = __builtin_bit_cast(bf16x8, w); }
;         f32x4 accO[16];
; #pragma unroll
;         for (int n = 0; n < 16; ++n) accO[n] = (f32x4){0.f, 0.f, 0.f, 0.f};
;         const int un = u + G;
; #pragma unroll
;         for (int k4 = 0; k4 < 4; ++k4) {
;             BAR_LDS();
;             XA_PUT_V();
;             if (k4 < 3) XA_FETCH(u, 5 + k4); else if (un < 2560) XA_FETCH(un, 0);
;             BAR_LDS();
; #pragma unroll
;             for (int kb = 0; kb < 2; ++kb)
; #pragma unroll
;                 for (int dtile = 0; dtile < 16; ++dtile) {
;                     const u32x2 lo = *(const LAS u32x2*)(Vs + (16 * dtile + fr) * VS + 32 * kb + 4 * fq), hi = *(const LAS u32x2*)(Vs + (16 * dtile + fr) * VS + 32 * kb + 16 + 4 * fq);
;                     accO[dtile] = __builtin_amdgcn_mfma_f32_16x16x32_bf16(mk8(lo, hi), pf[k4 * 2 + kb], accO[dtile], 0, 0, 0);
	v_sub_f32_e32 v28, v103, v4
	v_add_f32_e32 v8, v79, v8
	v_exp_f32_e32 v156, v28
	v_sub_f32_e32 v28, v104, v4
	v_add_f32_e32 v8, v117, v8
	v_exp_f32_e32 v157, v28
	v_sub_f32_e32 v28, v105, v4
	v_add_f32_e32 v8, v154, v8
	v_exp_f32_e32 v158, v28
	v_sub_f32_e32 v28, v106, v4
	v_add_f32_e32 v8, v155, v8
	v_exp_f32_e32 v159, v28
	v_sub_f32_e32 v28, v107, v4
	v_add_f32_e32 v8, v156, v8
	v_exp_f32_e32 v182, v28
	v_sub_f32_e32 v28, v108, v4
	v_add_f32_e32 v8, v157, v8
	v_exp_f32_e32 v183, v28
	v_sub_f32_e32 v28, v109, v4
	v_add_f32_e32 v8, v158, v8
	v_exp_f32_e32 v184, v28
	v_sub_f32_e32 v28, v110, v4
	v_add_f32_e32 v8, v159, v8
	v_exp_f32_e32 v185, v28
	v_sub_f32_e32 v28, v111, v4
	v_add_f32_e32 v8, v182, v8
	v_exp_f32_e32 v186, v28
	v_sub_f32_e32 v0, v0, v4
	v_add_f32_e32 v8, v183, v8
	v_exp_f32_e32 v187, v0
	v_cvt_pk_bf16_f32 v31, v14, v15
	v_cvt_pk_bf16_f32 v14, v40, v41
	v_mov_b64_e32 v[40:41], s[10:11]
	v_add_f32_e32 v8, v184, v8
	v_cvt_pk_bf16_f32 v30, v12, v13
	v_cvt_pk_bf16_f32 v20, v20, v21
	v_cvt_pk_bf16_f32 v21, v22, v23
	v_cvt_pk_bf16_f32 v22, v32, v33
	v_cvt_pk_bf16_f32 v12, v36, v37
	v_mad_i64_i32 v[24:25], s[10:11], v115, s24, v[40:41]
	v_mov_b32_e32 v115, v19
	v_mad_i64_i32 v[32:33], s[10:11], v122, s24, v[40:41]
	v_mad_i64_i32 v[36:37], s[10:11], v124, s24, v[40:41]
	v_mad_i64_i32 v[40:41], s[10:11], v126, s24, v[40:41]
	v_add_f32_e32 v8, v185, v8
	v_lshl_add_u64 v[120:121], v[24:25], 0, v[114:115]
	v_lshl_add_u64 v[122:123], v[32:33], 0, v[114:115]
	v_lshl_add_u64 v[124:125], v[36:37], 0, v[114:115]
	v_lshl_add_u64 v[126:127], v[40:41], 0, v[114:115]
	v_add_f32_e32 v8, v186, v8
	v_cvt_pk_bf16_f32 v23, v34, v35
	v_cvt_pk_bf16_f32 v13, v38, v39
	v_cvt_pk_bf16_f32 v15, v42, v43
	global_load_dwordx4 v[24:27], v[120:121], off offset:128
	global_load_dwordx4 v[32:35], v[122:123], off offset:128
	global_load_dwordx4 v[36:39], v[124:125], off offset:128
	global_load_dwordx4 v[40:43], v[126:127], off offset:128
	s_waitcnt lgkmcnt(0)
	s_barrier
	v_add_u32_e32 v115, 0x8000, v139
	v_add_f32_e32 v0, v187, v8
	v_cvt_pk_bf16_f32 v28, v7, v9
	v_cvt_pk_bf16_f32 v8, v44, v45
	v_cvt_pk_bf16_f32 v9, v46, v47
	ds_read2_b64 v[44:47], v115 offset0:128 offset1:132
	v_cvt_pk_bf16_f32 v29, v10, v11
	v_sub_f32_e32 v1, v1, v4
	v_exp_f32_e32 v188, v1
	s_waitcnt lgkmcnt(0)
	v_mfma_f32_16x16x32_bf16 v[52:55], v[44:47], v[28:31], 0
	ds_read2_b64 v[44:47], v193 offset0:128 offset1:132
	v_sub_f32_e32 v1, v2, v4
	v_exp_f32_e32 v189, v1
	s_waitcnt lgkmcnt(0)
	v_mfma_f32_16x16x32_bf16 v[56:59], v[44:47], v[28:31], 0
	ds_read2_b64 v[44:47], v194 offset0:128 offset1:132
	v_sub_f32_e32 v1, v3, v4
	v_exp_f32_e32 v190, v1
	s_waitcnt lgkmcnt(0)
	v_mfma_f32_16x16x32_bf16 v[60:63], v[44:47], v[28:31], 0
	ds_read2_b64 v[44:47], v195 offset0:128 offset1:132
	v_add_f32_e32 v0, v188, v0
	v_add_f32_e32 v0, v189, v0
	v_add_f32_e32 v0, v190, v0
	ds_bpermute_b32 v1, v5, v0
	v_cvt_pk_bf16_f32 v4, v64, v65
	v_cvt_pk_bf16_f32 v5, v66, v67
	s_waitcnt lgkmcnt(1)
	v_mfma_f32_16x16x32_bf16 v[64:67], v[44:47], v[28:31], 0
	ds_read2_b64 v[44:47], v196 offset0:192 offset1:196
	s_waitcnt lgkmcnt(1)
	v_add_f32_e32 v191, v0, v1
	ds_bpermute_b32 v192, v6, v191
	v_cvt_pk_bf16_f32 v6, v68, v69
	v_cvt_pk_bf16_f32 v7, v70, v71
	s_waitcnt lgkmcnt(1)
	v_mfma_f32_16x16x32_bf16 v[68:71], v[44:47], v[28:31], 0
	ds_read2_b64 v[44:47], v197 offset0:208 offset1:212
	v_cvt_pk_bf16_f32 v0, v72, v73
	v_cvt_pk_bf16_f32 v1, v74, v75
	s_waitcnt lgkmcnt(0)
	ds_read2_b64 v[208:211], v198 offset0:224 offset1:228
	ds_read2_b64 v[212:215], v199 offset0:240 offset1:244
	ds_read2_b64 v[216:219], v200 offset1:4
	ds_read2_b64 v[220:223], v201 offset0:16 offset1:20
	ds_read2_b64 v[224:227], v202 offset0:32 offset1:36
	ds_read2_b64 v[228:231], v203 offset0:48 offset1:52
	v_mfma_f32_16x16x32_bf16 v[72:75], v[44:47], v[28:31], 0
	v_cvt_pk_bf16_f32 v2, v76, v77
	v_cvt_pk_bf16_f32 v3, v78, v79
	ds_read2_b64 v[232:235], v204 offset0:64 offset1:68
	s_waitcnt lgkmcnt(6)
	v_mfma_f32_16x16x32_bf16 v[76:79], v[208:211], v[28:31], 0
	v_cvt_pk_bf16_f32 v10, v48, v49
	v_cvt_pk_bf16_f32 v11, v50, v51
	ds_read2_b64 v[236:239], v205 offset0:80 offset1:84
	s_waitcnt lgkmcnt(6)
	v_mfma_f32_16x16x32_bf16 v[80:83], v[212:215], v[28:31], 0
	ds_read2_b64 v[240:243], v206 offset0:96 offset1:100
	s_waitcnt lgkmcnt(6)
	v_mfma_f32_16x16x32_bf16 v[84:87], v[216:219], v[28:31], 0
	s_mov_b64 s[10:11], -1
	ds_read2_b64 v[244:247], v143 offset1:4
	s_waitcnt lgkmcnt(6)
	v_mfma_f32_16x16x32_bf16 v[88:91], v[220:223], v[28:31], 0
	ds_read2_b64 v[248:251], v115 offset0:136 offset1:140
	s_waitcnt lgkmcnt(6)
	v_mfma_f32_16x16x32_bf16 v[92:95], v[224:227], v[28:31], 0
	ds_read2_b64 v[208:211], v193 offset0:136 offset1:140
	s_waitcnt lgkmcnt(6)
	v_mfma_f32_16x16x32_bf16 v[96:99], v[228:231], v[28:31], 0
	ds_read2_b64 v[212:215], v194 offset0:136 offset1:140
	s_waitcnt lgkmcnt(6)
	v_mfma_f32_16x16x32_bf16 v[100:103], v[232:235], v[28:31], 0
	ds_read2_b64 v[216:219], v195 offset0:136 offset1:140
	s_waitcnt lgkmcnt(6)
	v_mfma_f32_16x16x32_bf16 v[44:47], v[236:239], v[28:31], 0
	ds_read2_b64 v[220:223], v196 offset0:200 offset1:204
	s_waitcnt lgkmcnt(6)
	v_mfma_f32_16x16x32_bf16 v[48:51], v[240:243], v[28:31], 0
	ds_read2_b64 v[224:227], v197 offset0:216 offset1:220
	s_waitcnt lgkmcnt(6)
	v_mfma_f32_16x16x32_bf16 v[28:31], v[244:247], v[28:31], 0
	ds_read2_b64 v[228:231], v198 offset0:232 offset1:236
	s_waitcnt lgkmcnt(6)
	v_mfma_f32_16x16x32_bf16 v[52:55], v[248:251], v[20:23], v[52:55]
	ds_read2_b64 v[232:235], v199 offset0:248 offset1:252
	s_waitcnt lgkmcnt(6)
	v_mfma_f32_16x16x32_bf16 v[56:59], v[208:211], v[20:23], v[56:59]
	ds_read2_b64 v[236:239], v200 offset0:8 offset1:12
	s_waitcnt lgkmcnt(6)
; #define LAS __attribute__((address_space(3)))
; #define BAR_LDS() do { asm volatile("s_waitcnt lgkmcnt(0)" ::: "memory"); __builtin_amdgcn_s_barrier(); asm volatile("" ::: "memory"); } while (0)
; #define XA_PUT_V() do { _Pragma("unroll") for (int i = 0; i < 4; ++i) { const int cidx = tid + 512 * i, r = cidx >> 3, c8 = cidx & 7; *(LAS u32x2*)(Vs + r * VS + c8 * 8) = (u32x2){stg[i].x, stg[i].y}; *(LAS u32x2*)(Vs + r * VS + c8 * 8 + 4) = (u32x2){stg[i].z, stg[i].w}; } } while (0)
; __device__ __forceinline__ void xattn_phase(KA a, LAS unsigned char* lds, int G, const int tid, const int bid) {
;     ...
;         for (int k4 = 0; k4 < 4; ++k4) {
;             BAR_LDS();
;             XA_PUT_V();
;             if (k4 < 3) XA_FETCH(u, 5 + k4); else if (un < 2560) XA_FETCH(un, 0);
;             BAR_LDS();
; #pragma unroll
;             for (int kb = 0; kb < 2; ++kb)
; #pragma unroll
;                 for (int dtile = 0; dtile < 16; ++dtile) {
;                     const u32x2 lo = *(const LAS u32x2*)(Vs + (16 * dtile + fr) * VS + 32 * kb + 4 * fq), hi = *(const LAS u32x2*)(Vs + (16 * dtile + fr) * VS + 32 * kb + 16 + 4 * fq);
;                     accO[dtile] = __builtin_amdgcn_mfma_f32_16x16x32_bf16(mk8(lo, hi), pf[k4 * 2 + kb], accO[dtile], 0, 0, 0);
;                 }
	v_mfma_f32_16x16x32_bf16 v[60:63], v[212:215], v[20:23], v[60:63]
	ds_read2_b64 v[240:243], v201 offset0:24 offset1:28
	s_waitcnt lgkmcnt(6)
	v_mfma_f32_16x16x32_bf16 v[64:67], v[216:219], v[20:23], v[64:67]
	ds_read2_b64 v[244:247], v202 offset0:40 offset1:44
	s_waitcnt lgkmcnt(6)
	v_mfma_f32_16x16x32_bf16 v[68:71], v[220:223], v[20:23], v[68:71]
	ds_read2_b64 v[248:251], v203 offset0:56 offset1:60
	s_waitcnt lgkmcnt(6)
	v_mfma_f32_16x16x32_bf16 v[72:75], v[224:227], v[20:23], v[72:75]
	ds_read2_b64 v[208:211], v204 offset0:72 offset1:76
	s_waitcnt lgkmcnt(6)
	v_mfma_f32_16x16x32_bf16 v[76:79], v[228:231], v[20:23], v[76:79]
	ds_read2_b64 v[212:215], v205 offset0:88 offset1:92
	s_waitcnt lgkmcnt(6)
	v_mfma_f32_16x16x32_bf16 v[80:83], v[232:235], v[20:23], v[80:83]
	ds_read2_b64 v[216:219], v206 offset0:104 offset1:108
	s_waitcnt lgkmcnt(6)
	v_mfma_f32_16x16x32_bf16 v[84:87], v[236:239], v[20:23], v[84:87]
	s_waitcnt lgkmcnt(5)
	v_mfma_f32_16x16x32_bf16 v[88:91], v[240:243], v[20:23], v[88:91]
	s_waitcnt lgkmcnt(4)
	v_mfma_f32_16x16x32_bf16 v[92:95], v[244:247], v[20:23], v[92:95]
	s_waitcnt lgkmcnt(3)
	v_mfma_f32_16x16x32_bf16 v[96:99], v[248:251], v[20:23], v[96:99]
	s_waitcnt lgkmcnt(2)
	v_mfma_f32_16x16x32_bf16 v[100:103], v[208:211], v[20:23], v[100:103]
	s_waitcnt lgkmcnt(1)
	v_mfma_f32_16x16x32_bf16 v[108:111], v[212:215], v[20:23], v[44:47]
	s_nop 2
	s_waitcnt lgkmcnt(0)
	v_mfma_f32_16x16x32_bf16 v[104:107], v[216:219], v[20:23], v[48:51]
	ds_read2_b64 v[220:223], v144 offset1:4
	s_waitcnt lgkmcnt(0)
	s_barrier
	s_waitcnt vmcnt(0)
	ds_write2_b64 v150, v[40:41], v[42:43] offset1:1
	ds_write2_b64 v151, v[36:37], v[38:39] offset1:1
	ds_write2_b64 v152, v[32:33], v[34:35] offset1:1
	ds_write2_b64 v153, v[24:25], v[26:27] offset1:1
	s_waitcnt lgkmcnt(4)
	v_mfma_f32_16x16x32_bf16 v[44:47], v[220:223], v[20:23], v[28:31]
	global_load_dwordx4 v[20:23], v[120:121], off offset:256
	global_load_dwordx4 v[24:27], v[122:123], off offset:256
	s_nop 0
	global_load_dwordx4 v[28:31], v[124:125], off offset:256
	global_load_dwordx4 v[32:35], v[126:127], off offset:256
	s_waitcnt lgkmcnt(0)
	s_barrier
	ds_read2_b64 v[244:247], v115 offset0:128 offset1:132
	ds_read2_b64 v[248:251], v193 offset0:128 offset1:132
	ds_read2_b64 v[208:211], v194 offset0:128 offset1:132
	ds_read2_b64 v[212:215], v195 offset0:128 offset1:132
	ds_read2_b64 v[216:219], v196 offset0:192 offset1:196
	ds_read2_b64 v[220:223], v197 offset0:208 offset1:212
	ds_read2_b64 v[224:227], v198 offset0:224 offset1:228
	s_waitcnt lgkmcnt(6)
	v_mfma_f32_16x16x32_bf16 v[48:51], v[244:247], v[12:15], v[52:55]
	ds_read2_b64 v[228:231], v199 offset0:240 offset1:244
	s_waitcnt lgkmcnt(6)
	v_mfma_f32_16x16x32_bf16 v[52:55], v[248:251], v[12:15], v[56:59]
	ds_read2_b64 v[232:235], v200 offset1:4
	s_waitcnt lgkmcnt(6)
	v_mfma_f32_16x16x32_bf16 v[56:59], v[208:211], v[12:15], v[60:63]
	ds_read2_b64 v[236:239], v201 offset0:16 offset1:20
	s_waitcnt lgkmcnt(6)
	v_mfma_f32_16x16x32_bf16 v[60:63], v[212:215], v[12:15], v[64:67]
	ds_read2_b64 v[240:243], v202 offset0:32 offset1:36
	s_waitcnt lgkmcnt(6)
	v_mfma_f32_16x16x32_bf16 v[64:67], v[216:219], v[12:15], v[68:71]
	ds_read2_b64 v[244:247], v203 offset0:48 offset1:52
	s_waitcnt lgkmcnt(6)
	v_mfma_f32_16x16x32_bf16 v[68:71], v[220:223], v[12:15], v[72:75]
	ds_read2_b64 v[248:251], v204 offset0:64 offset1:68
	s_waitcnt lgkmcnt(6)
	v_mfma_f32_16x16x32_bf16 v[72:75], v[224:227], v[12:15], v[76:79]
	ds_read2_b64 v[208:211], v205 offset0:80 offset1:84
	s_waitcnt lgkmcnt(6)
	v_mfma_f32_16x16x32_bf16 v[76:79], v[228:231], v[12:15], v[80:83]
	ds_read2_b64 v[212:215], v206 offset0:96 offset1:100
	s_waitcnt lgkmcnt(6)
	v_mfma_f32_16x16x32_bf16 v[80:83], v[232:235], v[12:15], v[84:87]
	ds_read2_b64 v[216:219], v143 offset1:4
	s_waitcnt lgkmcnt(6)
	v_mfma_f32_16x16x32_bf16 v[84:87], v[236:239], v[12:15], v[88:91]
	ds_read2_b64 v[220:223], v115 offset0:136 offset1:140
	s_waitcnt lgkmcnt(6)
	v_mfma_f32_16x16x32_bf16 v[88:91], v[240:243], v[12:15], v[92:95]
	ds_read2_b64 v[224:227], v193 offset0:136 offset1:140
	s_waitcnt lgkmcnt(6)
	v_mfma_f32_16x16x32_bf16 v[92:95], v[244:247], v[12:15], v[96:99]
	ds_read2_b64 v[228:231], v194 offset0:136 offset1:140
	s_waitcnt lgkmcnt(6)
	v_mfma_f32_16x16x32_bf16 v[96:99], v[248:251], v[12:15], v[100:103]
	s_nop 1
	ds_read2_b64 v[232:235], v195 offset0:136 offset1:140
	s_waitcnt lgkmcnt(6)
	v_mfma_f32_16x16x32_bf16 v[36:39], v[208:211], v[12:15], v[108:111]
	ds_read2_b64 v[236:239], v196 offset0:200 offset1:204
	s_waitcnt lgkmcnt(6)
	v_mfma_f32_16x16x32_bf16 v[40:43], v[212:215], v[12:15], v[104:107]
	ds_read2_b64 v[240:243], v197 offset0:216 offset1:220
	s_waitcnt lgkmcnt(6)
	v_mfma_f32_16x16x32_bf16 v[12:15], v[216:219], v[12:15], v[44:47]
	s_nop 2
	ds_read2_b64 v[244:247], v198 offset0:232 offset1:236
	s_waitcnt lgkmcnt(6)
	v_mfma_f32_16x16x32_bf16 v[44:47], v[220:223], v[8:11], v[48:51]
	s_nop 2
	ds_read2_b64 v[248:251], v199 offset0:248 offset1:252
	s_waitcnt lgkmcnt(6)
	v_mfma_f32_16x16x32_bf16 v[48:51], v[224:227], v[8:11], v[52:55]
	s_nop 2
	ds_read2_b64 v[208:211], v200 offset0:8 offset1:12
	s_waitcnt lgkmcnt(6)
	v_mfma_f32_16x16x32_bf16 v[52:55], v[228:231], v[8:11], v[56:59]
	s_nop 2
	ds_read2_b64 v[212:215], v201 offset0:24 offset1:28
	s_waitcnt lgkmcnt(6)
	v_mfma_f32_16x16x32_bf16 v[56:59], v[232:235], v[8:11], v[60:63]
	s_nop 2
	ds_read2_b64 v[216:219], v202 offset0:40 offset1:44
	s_waitcnt lgkmcnt(6)
	v_mfma_f32_16x16x32_bf16 v[60:63], v[236:239], v[8:11], v[64:67]
	s_nop 2
	ds_read2_b64 v[220:223], v203 offset0:56 offset1:60
	s_waitcnt lgkmcnt(6)
	v_mfma_f32_16x16x32_bf16 v[64:67], v[240:243], v[8:11], v[68:71]
	s_nop 2
	ds_read2_b64 v[224:227], v204 offset0:72 offset1:76
	s_waitcnt lgkmcnt(6)
	v_mfma_f32_16x16x32_bf16 v[68:71], v[244:247], v[8:11], v[72:75]
	s_nop 2
	ds_read2_b64 v[228:231], v205 offset0:88 offset1:92
	s_waitcnt lgkmcnt(6)
	v_mfma_f32_16x16x32_bf16 v[72:75], v[248:251], v[8:11], v[76:79]
	s_nop 2
	ds_read2_b64 v[232:235], v206 offset0:104 offset1:108
	s_waitcnt lgkmcnt(6)
	v_mfma_f32_16x16x32_bf16 v[76:79], v[208:211], v[8:11], v[80:83]
	s_nop 2
	s_waitcnt lgkmcnt(5)
	v_mfma_f32_16x16x32_bf16 v[80:83], v[212:215], v[8:11], v[84:87]
	s_nop 2
	s_waitcnt lgkmcnt(4)
	v_mfma_f32_16x16x32_bf16 v[84:87], v[216:219], v[8:11], v[88:91]
	s_nop 2
	s_waitcnt lgkmcnt(3)
	v_mfma_f32_16x16x32_bf16 v[88:91], v[220:223], v[8:11], v[92:95]
	s_nop 2
	s_waitcnt lgkmcnt(2)
	v_mfma_f32_16x16x32_bf16 v[92:95], v[224:227], v[8:11], v[96:99]
	s_nop 2
	s_waitcnt lgkmcnt(1)
	v_mfma_f32_16x16x32_bf16 v[100:103], v[228:231], v[8:11], v[36:39]
	s_nop 2
	s_waitcnt lgkmcnt(0)
	v_mfma_f32_16x16x32_bf16 v[96:99], v[232:235], v[8:11], v[40:43]
	ds_read2_b64 v[236:239], v144 offset1:4
	s_waitcnt lgkmcnt(0)
	s_barrier
; #define LAS __attribute__((address_space(3)))
; #define BAR_LDS() do { asm volatile("s_waitcnt lgkmcnt(0)" ::: "memory"); __builtin_amdgcn_s_barrier(); asm volatile("" ::: "memory"); } while (0)
; #define XA_PUT_V() do { _Pragma("unroll") for (int i = 0; i < 4; ++i) { const int cidx = tid + 512 * i, r = cidx >> 3, c8 = cidx & 7; *(LAS u32x2*)(Vs + r * VS + c8 * 8) = (u32x2){stg[i].x, stg[i].y}; *(LAS u32x2*)(Vs + r * VS + c8 * 8 + 4) = (u32x2){stg[i].z, stg[i].w}; } } while (0)
; __device__ __forceinline__ void xattn_phase(KA a, LAS unsigned char* lds, int G, const int tid, const int bid) {
;     ...
;         for (int k4 = 0; k4 < 4; ++k4) {
;             BAR_LDS();
;             XA_PUT_V();
;             if (k4 < 3) XA_FETCH(u, 5 + k4); else if (un < 2560) XA_FETCH(un, 0);
;             BAR_LDS();
; #pragma unroll
;             for (int kb = 0; kb < 2; ++kb)
; #pragma unroll
;                 for (int dtile = 0; dtile < 16; ++dtile) {
;                     const u32x2 lo = *(const LAS u32x2*)(Vs + (16 * dtile + fr) * VS + 32 * kb + 4 * fq), hi = *(const LAS u32x2*)(Vs + (16 * dtile + fr) * VS + 32 * kb + 16 + 4 * fq);
;                     accO[dtile] = __builtin_amdgcn_mfma_f32_16x16x32_bf16(mk8(lo, hi), pf[k4 * 2 + kb], accO[dtile], 0, 0, 0);
;                 }
;         }
	s_waitcnt vmcnt(0)
	ds_write2_b64 v150, v[32:33], v[34:35] offset1:1
	ds_write2_b64 v151, v[28:29], v[30:31] offset1:1
	ds_write2_b64 v152, v[24:25], v[26:27] offset1:1
	ds_write2_b64 v153, v[20:21], v[22:23] offset1:1
	s_waitcnt lgkmcnt(4)
	v_mfma_f32_16x16x32_bf16 v[36:39], v[236:239], v[8:11], v[12:15]
	global_load_dwordx4 v[20:23], v[126:127], off offset:384
	global_load_dwordx4 v[24:27], v[124:125], off offset:384
	global_load_dwordx4 v[8:11], v[122:123], off offset:384
	global_load_dwordx4 v[12:15], v[120:121], off offset:384
	s_waitcnt lgkmcnt(0)
	s_barrier
	ds_read2_b64 v[240:243], v115 offset0:128 offset1:132
	ds_read2_b64 v[244:247], v194 offset0:128 offset1:132
	ds_read2_b64 v[248:251], v195 offset0:128 offset1:132
	ds_read2_b64 v[208:211], v193 offset0:128 offset1:132
	ds_read2_b64 v[212:215], v197 offset0:208 offset1:212
	ds_read2_b64 v[216:219], v198 offset0:224 offset1:228
	ds_read2_b64 v[220:223], v196 offset0:192 offset1:196
	s_waitcnt lgkmcnt(6)
	v_mfma_f32_16x16x32_bf16 v[28:31], v[240:243], v[4:7], v[44:47]
	s_nop 1
	ds_read2_b64 v[224:227], v200 offset1:4
	s_waitcnt lgkmcnt(6)
	v_mfma_f32_16x16x32_bf16 v[40:43], v[244:247], v[4:7], v[52:55]
	s_nop 2
	ds_read2_b64 v[228:231], v201 offset0:16 offset1:20
	s_waitcnt lgkmcnt(6)
	v_mfma_f32_16x16x32_bf16 v[44:47], v[248:251], v[4:7], v[56:59]
	s_nop 2
	ds_read2_b64 v[232:235], v199 offset0:240 offset1:244
	s_waitcnt lgkmcnt(6)
	v_mfma_f32_16x16x32_bf16 v[32:35], v[208:211], v[4:7], v[48:51]
	s_nop 2
	ds_read2_b64 v[236:239], v203 offset0:48 offset1:52
	s_waitcnt lgkmcnt(6)
	v_mfma_f32_16x16x32_bf16 v[52:55], v[212:215], v[4:7], v[64:67]
	ds_read2_b64 v[240:243], v204 offset0:64 offset1:68
	s_waitcnt lgkmcnt(6)
	v_mfma_f32_16x16x32_bf16 v[56:59], v[216:219], v[4:7], v[68:71]
	s_nop 0
	s_nop 0
	ds_read2_b64 v[244:247], v202 offset0:32 offset1:36
	s_waitcnt lgkmcnt(6)
	v_mfma_f32_16x16x32_bf16 v[48:51], v[220:223], v[4:7], v[60:63]
	s_nop 2
	ds_read2_b64 v[248:251], v205 offset0:80 offset1:84
	s_waitcnt lgkmcnt(6)
	v_mfma_f32_16x16x32_bf16 v[64:67], v[224:227], v[4:7], v[76:79]
	ds_read2_b64 v[208:211], v206 offset0:96 offset1:100
	s_waitcnt lgkmcnt(6)
	v_mfma_f32_16x16x32_bf16 v[68:71], v[228:231], v[4:7], v[80:83]
	s_nop 0
	s_nop 0
	ds_read2_b64 v[212:215], v143 offset1:4
	s_waitcnt lgkmcnt(6)
	v_mfma_f32_16x16x32_bf16 v[60:63], v[232:235], v[4:7], v[72:75]
	s_nop 2
	ds_read2_b64 v[216:219], v115 offset0:136 offset1:140
	s_waitcnt lgkmcnt(6)
	v_mfma_f32_16x16x32_bf16 v[76:79], v[236:239], v[4:7], v[88:91]
	ds_read2_b64 v[220:223], v193 offset0:136 offset1:140
	s_waitcnt lgkmcnt(6)
	v_mfma_f32_16x16x32_bf16 v[88:91], v[240:243], v[4:7], v[92:95]
	ds_read2_b64 v[224:227], v194 offset0:136 offset1:140
	s_waitcnt lgkmcnt(6)
	v_mfma_f32_16x16x32_bf16 v[72:75], v[244:247], v[4:7], v[84:87]
	ds_read2_b64 v[228:231], v196 offset0:200 offset1:204
	s_waitcnt lgkmcnt(6)
	v_mfma_f32_16x16x32_bf16 v[92:95], v[248:251], v[4:7], v[100:103]
	ds_read2_b64 v[232:235], v195 offset0:136 offset1:140
	s_waitcnt lgkmcnt(6)
	v_mfma_f32_16x16x32_bf16 v[80:83], v[208:211], v[4:7], v[96:99]
	ds_read2_b64 v[236:239], v198 offset0:232 offset1:236
	s_waitcnt lgkmcnt(6)
	v_mfma_f32_16x16x32_bf16 v[84:87], v[212:215], v[4:7], v[36:39]
	ds_read2_b64 v[240:243], v197 offset0:216 offset1:220
	s_waitcnt lgkmcnt(6)
	v_mfma_f32_16x16x32_bf16 v[4:7], v[216:219], v[0:3], v[28:31]
	s_nop 2
	ds_read2_b64 v[244:247], v200 offset0:8 offset1:12
	s_waitcnt lgkmcnt(6)
	v_mfma_f32_16x16x32_bf16 v[32:35], v[220:223], v[0:3], v[32:35]
	ds_read2_b64 v[248:251], v199 offset0:248 offset1:252
	s_waitcnt lgkmcnt(6)
	v_mfma_f32_16x16x32_bf16 v[28:31], v[224:227], v[0:3], v[40:43]
	s_nop 2
	ds_read2_b64 v[208:211], v202 offset0:40 offset1:44
	s_waitcnt lgkmcnt(6)
	v_mfma_f32_16x16x32_bf16 v[40:43], v[228:231], v[0:3], v[48:51]
	s_nop 2
	ds_read2_b64 v[212:215], v201 offset0:24 offset1:28
	s_waitcnt lgkmcnt(6)
	v_mfma_f32_16x16x32_bf16 v[36:39], v[232:235], v[0:3], v[44:47]
	s_nop 2
	ds_read2_b64 v[216:219], v204 offset0:72 offset1:76
	s_waitcnt lgkmcnt(6)
	v_mfma_f32_16x16x32_bf16 v[48:51], v[236:239], v[0:3], v[56:59]
	s_nop 2
	ds_read2_b64 v[220:223], v203 offset0:56 offset1:60
	s_waitcnt lgkmcnt(6)
	v_mfma_f32_16x16x32_bf16 v[44:47], v[240:243], v[0:3], v[52:55]
	s_nop 2
	ds_read2_b64 v[224:227], v206 offset0:104 offset1:108
	s_waitcnt lgkmcnt(6)
	v_mfma_f32_16x16x32_bf16 v[56:59], v[244:247], v[0:3], v[64:67]
	s_nop 2
	s_waitcnt lgkmcnt(5)
	v_mfma_f32_16x16x32_bf16 v[52:55], v[248:251], v[0:3], v[60:63]
	s_nop 2
	s_waitcnt lgkmcnt(4)
	v_mfma_f32_16x16x32_bf16 v[64:67], v[208:211], v[0:3], v[72:75]
	s_nop 2
	s_waitcnt lgkmcnt(3)
	v_mfma_f32_16x16x32_bf16 v[60:63], v[212:215], v[0:3], v[68:71]
	s_nop 2
	s_waitcnt lgkmcnt(2)
	v_mfma_f32_16x16x32_bf16 v[72:75], v[216:219], v[0:3], v[88:91]
	s_nop 2
	s_waitcnt lgkmcnt(1)
	v_mfma_f32_16x16x32_bf16 v[68:71], v[220:223], v[0:3], v[76:79]
	s_nop 2
	s_waitcnt lgkmcnt(0)
	v_mfma_f32_16x16x32_bf16 v[80:83], v[224:227], v[0:3], v[80:83]
	ds_read2_b64 v[228:231], v205 offset0:88 offset1:92
	ds_read2_b64 v[232:235], v144 offset1:4
	s_waitcnt lgkmcnt(0)
	s_barrier
	s_waitcnt lgkmcnt(1)
	v_mfma_f32_16x16x32_bf16 v[76:79], v[228:231], v[0:3], v[92:95]
	s_waitcnt vmcnt(3)
	ds_write2_b64 v150, v[20:21], v[22:23] offset1:1
	s_waitcnt vmcnt(2)
	ds_write2_b64 v151, v[24:25], v[26:27] offset1:1
	s_waitcnt vmcnt(1)
	ds_write2_b64 v152, v[8:9], v[10:11] offset1:1
	s_waitcnt vmcnt(0)
	ds_write2_b64 v153, v[12:13], v[14:15] offset1:1
	s_waitcnt lgkmcnt(4)
	v_mfma_f32_16x16x32_bf16 v[84:87], v[232:235], v[0:3], v[84:87]
	s_cbranch_scc1 .LBB0_116
	s_add_i32 s20, s19, s14
	s_add_i32 s21, s18, s15
	s_mov_b64 s[10:11], 0
